# v7: + GLA c-tile divisions as rcp*mul, final RMSNorm row loads batched
# speedup vs baseline: 1.0181x; 1.0005x over previous
; __device__ __forceinline__ void gla_a_tile(LAS unsigned char* lds, const GlaArgs& A, int tile, int tid) {
;     ...
;     if (tid < 64) A.dec[((size_t)bh * 64 + n) * 64 + tid] = __expf(GC[63 * 65 + tid]);
.LBB0_197:
	s_or_b64 exec, exec, s[22:23]
	s_and_saveexec_b64 s[20:21], s[18:19]
	s_cbranch_execz .LBB0_191
	ds_read_b32 v2, v124 offset:16380
	s_waitcnt lgkmcnt(0)
	v_mul_f32_e32 v2, 0x3fb8aa3b, v2
	v_exp_f32_e32 v2, v2
	s_nop 0
	global_store_dword v[88:89], v2, off
	s_branch .LBB0_191

; #define LAS __attribute__((address_space(3)))
; __device__ __forceinline__ unsigned cvt_pk_bf16(float lo, float hi) { const f32x2 v = {lo, hi}; const bf16x2_t r = __builtin_convertvector(v, bf16x2_t); return __builtin_bit_cast(unsigned, r); }
; __device__ __forceinline__ void gla_c_tile(LAS unsigned char* lds, const GlaArgs& A, int tile, int tid) {
;     ...
;           for (int e = 0; e < 8; ++e) { const int i = i0 + 8 * e; f32x4 x1, x2;
; #pragma unroll
;               for (int q = 0; q < 4; ++q) { const float eg = __expf(GC[i * 65 + d + q]); const float x = o[e][q] * sc; x1[q] = x * eg; x2[q] = x / eg; }
;               u32x2 w1, w2; w1.x = cvt_pk_bf16(x1[0], x1[1]); w1.y = cvt_pk_bf16(x1[2], x1[3]); w2.x = cvt_pk_bf16(x2[0], x2[1]); w2.y = cvt_pk_bf16(x2[2], x2[3]);
;               *(LAS u32x2*)(T1 + i * 72 + d) = w1; *(LAS u32x2*)(T2 + i * 72 + d) = w2; } }
.LBB0_312:
	s_andn2_saveexec_b64 s[38:39], s[38:39]
	s_cbranch_execz .LBB0_314
	v_add_u32_e32 v16, v139, v133
	ds_read2_b32 v[10:11], v16 offset1:1
	v_pk_mul_f32 v[14:15], v[98:99], v[50:51]
	v_pk_mul_f32 v[6:7], v[98:99], v[6:7]
	v_pk_mul_f32 v[2:3], v[98:99], v[2:3]
	s_waitcnt lgkmcnt(0)
	v_mul_f32_e32 v10, 0x3fb8aa3b, v10
	v_exp_f32_e32 v12, v10
	v_mul_f32_e32 v10, 0x3fb8aa3b, v11
	v_exp_f32_e32 v13, v10
	s_nop 0
	v_pk_mul_f32 v[10:11], v[14:15], v[12:13]
	v_rcp_f32_e32 v17, v13
	s_nop 0
	v_mul_f32_e32 v40, v15, v17
	v_cvt_pk_bf16_f32 v10, v10, v11
	v_rcp_f32_e32 v13, v12
	s_nop 0
	v_mul_f32_e32 v41, v14, v13
	ds_read2_b32 v[12:13], v16 offset0:2 offset1:3
	v_pk_mul_f32 v[14:15], v[98:99], v[38:39]
	s_waitcnt lgkmcnt(0)
	v_mul_f32_e32 v13, 0x3fb8aa3b, v13
	v_exp_f32_e32 v13, v13
	v_mul_f32_e32 v12, 0x3fb8aa3b, v12
	v_exp_f32_e32 v12, v12
	s_nop 0
	v_pk_mul_f32 v[16:17], v[14:15], v[12:13]
	v_rcp_f32_e32 v38, v13
	s_nop 0
	v_mul_f32_e32 v13, v15, v38
	v_cvt_pk_bf16_f32 v11, v16, v17
	v_rcp_f32_e32 v15, v12
	s_nop 0
	v_mul_f32_e32 v14, v14, v15
	v_cvt_pk_bf16_f32 v12, v41, v40
	v_cvt_pk_bf16_f32 v13, v14, v13
	ds_write_b64 v140, v[10:11]
	ds_write_b64 v141, v[12:13]
	ds_read2_b32 v[10:11], v147 offset1:1
	v_pk_mul_f32 v[14:15], v[98:99], v[36:37]
	s_waitcnt lgkmcnt(0)
	v_mul_f32_e32 v10, 0x3fb8aa3b, v10
	v_exp_f32_e32 v12, v10
	v_mul_f32_e32 v10, 0x3fb8aa3b, v11
	v_exp_f32_e32 v13, v10
	s_nop 0
	v_pk_mul_f32 v[10:11], v[14:15], v[12:13]
	v_rcp_f32_e32 v16, v13
	s_nop 0
	v_mul_f32_e32 v36, v15, v16
	v_cvt_pk_bf16_f32 v10, v10, v11
	v_rcp_f32_e32 v13, v12
	s_nop 0
	v_mul_f32_e32 v37, v14, v13
	ds_read2_b32 v[12:13], v147 offset0:2 offset1:3
	v_pk_mul_f32 v[14:15], v[98:99], v[32:33]
	s_waitcnt lgkmcnt(0)
	v_mul_f32_e32 v13, 0x3fb8aa3b, v13
	v_exp_f32_e32 v13, v13
	v_mul_f32_e32 v12, 0x3fb8aa3b, v12
	v_exp_f32_e32 v12, v12
	s_nop 0
	v_pk_mul_f32 v[16:17], v[14:15], v[12:13]
	v_rcp_f32_e32 v32, v13
	s_nop 0
	v_mul_f32_e32 v13, v15, v32
	v_cvt_pk_bf16_f32 v11, v16, v17
	v_rcp_f32_e32 v15, v12
	s_nop 0
	v_mul_f32_e32 v14, v14, v15
	v_cvt_pk_bf16_f32 v12, v37, v36
	v_cvt_pk_bf16_f32 v13, v14, v13
	ds_write_b64 v140, v[10:11] offset:1152
	ds_write_b64 v141, v[12:13] offset:1152
	v_add_u32_e32 v10, 0x820, v147
	ds_read2_b32 v[10:11], v10 offset1:1
	v_pk_mul_f32 v[14:15], v[98:99], v[34:35]
	s_waitcnt lgkmcnt(0)
	v_mul_f32_e32 v10, 0x3fb8aa3b, v10
	v_exp_f32_e32 v12, v10
	v_mul_f32_e32 v10, 0x3fb8aa3b, v11
	v_exp_f32_e32 v13, v10
	s_nop 0
	v_pk_mul_f32 v[10:11], v[14:15], v[12:13]
	v_rcp_f32_e32 v16, v13
	s_nop 0
	v_mul_f32_e32 v32, v15, v16
	v_cvt_pk_bf16_f32 v10, v10, v11
	v_rcp_f32_e32 v13, v12
	s_nop 0
	v_mul_f32_e32 v33, v14, v13
	v_add_u32_e32 v12, 0x828, v147
	ds_read2_b32 v[12:13], v12 offset1:1
	v_pk_mul_f32 v[14:15], v[98:99], v[30:31]
	s_waitcnt lgkmcnt(0)
	v_mul_f32_e32 v13, 0x3fb8aa3b, v13
	v_exp_f32_e32 v13, v13
	v_mul_f32_e32 v12, 0x3fb8aa3b, v12
	v_exp_f32_e32 v12, v12
	s_nop 0
	v_pk_mul_f32 v[16:17], v[14:15], v[12:13]
	v_rcp_f32_e32 v30, v13
	s_nop 0
	v_mul_f32_e32 v13, v15, v30
	v_cvt_pk_bf16_f32 v11, v16, v17
	v_rcp_f32_e32 v15, v12
	s_nop 0
	v_mul_f32_e32 v14, v14, v15
	v_cvt_pk_bf16_f32 v12, v33, v32
	v_cvt_pk_bf16_f32 v13, v14, v13
	ds_write_b64 v140, v[10:11] offset:2304
	ds_write_b64 v141, v[12:13] offset:2304
	v_add_u32_e32 v10, 0x1040, v147
	ds_read2_b32 v[10:11], v10 offset1:1
	v_pk_mul_f32 v[14:15], v[98:99], v[28:29]
	s_waitcnt lgkmcnt(0)
	v_mul_f32_e32 v10, 0x3fb8aa3b, v10
	v_exp_f32_e32 v12, v10
	v_mul_f32_e32 v10, 0x3fb8aa3b, v11
	v_exp_f32_e32 v13, v10
	s_nop 0
	v_pk_mul_f32 v[10:11], v[14:15], v[12:13]
	v_rcp_f32_e32 v16, v13
	s_nop 0
	v_mul_f32_e32 v28, v15, v16
	v_cvt_pk_bf16_f32 v10, v10, v11
	v_rcp_f32_e32 v13, v12
	s_nop 0
	v_mul_f32_e32 v29, v14, v13
	v_add_u32_e32 v12, 0x1048, v147
	ds_read2_b32 v[12:13], v12 offset1:1
	v_pk_mul_f32 v[14:15], v[98:99], v[24:25]
	s_waitcnt lgkmcnt(0)
	v_mul_f32_e32 v13, 0x3fb8aa3b, v13
	v_exp_f32_e32 v13, v13
	v_mul_f32_e32 v12, 0x3fb8aa3b, v12
	v_exp_f32_e32 v12, v12
	s_nop 0
	v_pk_mul_f32 v[16:17], v[14:15], v[12:13]
	v_rcp_f32_e32 v24, v13
	s_nop 0
	v_mul_f32_e32 v13, v15, v24
	v_cvt_pk_bf16_f32 v11, v16, v17
	v_rcp_f32_e32 v15, v12
	s_nop 0
	v_mul_f32_e32 v14, v14, v15
	v_cvt_pk_bf16_f32 v12, v29, v28
	v_cvt_pk_bf16_f32 v13, v14, v13
	ds_write_b64 v140, v[10:11] offset:3456
	ds_write_b64 v141, v[12:13] offset:3456
	v_add_u32_e32 v10, 0x1860, v147
	ds_read2_b32 v[10:11], v10 offset1:1
	v_pk_mul_f32 v[14:15], v[98:99], v[26:27]
	s_waitcnt lgkmcnt(0)
; #define LAS __attribute__((address_space(3)))
; __device__ __forceinline__ unsigned cvt_pk_bf16(float lo, float hi) { const f32x2 v = {lo, hi}; const bf16x2_t r = __builtin_convertvector(v, bf16x2_t); return __builtin_bit_cast(unsigned, r); }
; __device__ __forceinline__ void gla_c_tile(LAS unsigned char* lds, const GlaArgs& A, int tile, int tid) {
;     ...
;           for (int e = 0; e < 8; ++e) { const int i = i0 + 8 * e; f32x4 x1, x2;
; #pragma unroll
;               for (int q = 0; q < 4; ++q) { const float eg = __expf(GC[i * 65 + d + q]); const float x = o[e][q] * sc; x1[q] = x * eg; x2[q] = x / eg; }
;               u32x2 w1, w2; w1.x = cvt_pk_bf16(x1[0], x1[1]); w1.y = cvt_pk_bf16(x1[2], x1[3]); w2.x = cvt_pk_bf16(x2[0], x2[1]); w2.y = cvt_pk_bf16(x2[2], x2[3]);
;               *(LAS u32x2*)(T1 + i * 72 + d) = w1; *(LAS u32x2*)(T2 + i * 72 + d) = w2; } }
	v_mul_f32_e32 v10, 0x3fb8aa3b, v10
	v_exp_f32_e32 v12, v10
	v_mul_f32_e32 v10, 0x3fb8aa3b, v11
	v_exp_f32_e32 v13, v10
	s_nop 0
	v_pk_mul_f32 v[10:11], v[14:15], v[12:13]
	v_rcp_f32_e32 v16, v13
	s_nop 0
	v_mul_f32_e32 v24, v15, v16
	v_cvt_pk_bf16_f32 v10, v10, v11
	v_rcp_f32_e32 v13, v12
	s_nop 0
	v_mul_f32_e32 v25, v14, v13
	v_add_u32_e32 v12, 0x1868, v147
	ds_read2_b32 v[12:13], v12 offset1:1
	v_pk_mul_f32 v[14:15], v[98:99], v[22:23]
	s_waitcnt lgkmcnt(0)
	v_mul_f32_e32 v13, 0x3fb8aa3b, v13
	v_exp_f32_e32 v13, v13
	v_mul_f32_e32 v12, 0x3fb8aa3b, v12
	v_exp_f32_e32 v12, v12
	s_nop 0
	v_pk_mul_f32 v[16:17], v[14:15], v[12:13]
	v_rcp_f32_e32 v22, v13
	s_nop 0
	v_mul_f32_e32 v13, v15, v22
	v_cvt_pk_bf16_f32 v11, v16, v17
	v_rcp_f32_e32 v15, v12
	s_nop 0
	v_mul_f32_e32 v14, v14, v15
	v_cvt_pk_bf16_f32 v12, v25, v24
	v_cvt_pk_bf16_f32 v13, v14, v13
	ds_write_b64 v140, v[10:11] offset:4608
	ds_write_b64 v141, v[12:13] offset:4608
	v_add_u32_e32 v10, 0x2080, v147
	ds_read2_b32 v[10:11], v10 offset1:1
	v_pk_mul_f32 v[14:15], v[98:99], v[20:21]
	s_waitcnt lgkmcnt(0)
	v_mul_f32_e32 v10, 0x3fb8aa3b, v10
	v_exp_f32_e32 v12, v10
	v_mul_f32_e32 v10, 0x3fb8aa3b, v11
	v_exp_f32_e32 v13, v10
	s_nop 0
	v_pk_mul_f32 v[10:11], v[14:15], v[12:13]
	v_rcp_f32_e32 v16, v13
	s_nop 0
	v_mul_f32_e32 v20, v15, v16
	v_cvt_pk_bf16_f32 v10, v10, v11
	v_rcp_f32_e32 v13, v12
	s_nop 0
	v_mul_f32_e32 v21, v14, v13
	v_add_u32_e32 v12, 0x2088, v147
	ds_read2_b32 v[12:13], v12 offset1:1
	v_pk_mul_f32 v[14:15], v[98:99], v[18:19]
	s_waitcnt lgkmcnt(0)
	v_mul_f32_e32 v13, 0x3fb8aa3b, v13
	v_exp_f32_e32 v13, v13
	v_mul_f32_e32 v12, 0x3fb8aa3b, v12
	v_exp_f32_e32 v12, v12
	s_nop 0
	v_pk_mul_f32 v[16:17], v[14:15], v[12:13]
	v_rcp_f32_e32 v18, v13
	s_nop 0
	v_mul_f32_e32 v13, v15, v18
	v_cvt_pk_bf16_f32 v11, v16, v17
	v_rcp_f32_e32 v15, v12
	s_nop 0
	v_mul_f32_e32 v14, v14, v15
	v_cvt_pk_bf16_f32 v12, v21, v20
	v_cvt_pk_bf16_f32 v13, v14, v13
	ds_write_b64 v140, v[10:11] offset:5760
	ds_write_b64 v141, v[12:13] offset:5760
	v_add_u32_e32 v10, 0x28a0, v147
	ds_read2_b32 v[10:11], v10 offset1:1
	v_pk_mul_f32 v[12:13], v[98:99], v[8:9]
	s_waitcnt lgkmcnt(0)
	v_mul_f32_e32 v8, 0x3fb8aa3b, v11
	v_exp_f32_e32 v11, v8
	v_mul_f32_e32 v10, 0x3fb8aa3b, v10
	v_exp_f32_e32 v10, v10
	s_nop 0
	v_pk_mul_f32 v[8:9], v[12:13], v[10:11]
	v_rcp_f32_e32 v14, v11
	s_nop 0
	v_mul_f32_e32 v14, v13, v14
	s_nop 0
	v_rcp_f32_e32 v11, v10
	s_nop 0
	v_mul_f32_e32 v15, v12, v11
	v_add_u32_e32 v10, 0x28a8, v147
	ds_read2_b32 v[10:11], v10 offset1:1
	s_waitcnt lgkmcnt(0)
	v_mul_f32_e32 v11, 0x3fb8aa3b, v11
	v_exp_f32_e32 v11, v11
	v_mul_f32_e32 v10, 0x3fb8aa3b, v10
	v_exp_f32_e32 v10, v10
	s_nop 0
	v_pk_mul_f32 v[12:13], v[6:7], v[10:11]
	v_rcp_f32_e32 v16, v11
	s_nop 0
	v_mul_f32_e32 v11, v7, v16
	s_nop 0
	v_rcp_f32_e32 v7, v10
	s_nop 0
	v_mul_f32_e32 v10, v6, v7
	v_cvt_pk_bf16_f32 v6, v8, v9
	v_cvt_pk_bf16_f32 v7, v12, v13
	v_cvt_pk_bf16_f32 v8, v15, v14
	v_cvt_pk_bf16_f32 v9, v10, v11
	ds_write_b64 v140, v[6:7] offset:6912
	ds_write_b64 v141, v[8:9] offset:6912
	v_add_u32_e32 v6, 0x30c0, v147
	ds_read2_b32 v[6:7], v6 offset1:1
	v_pk_mul_f32 v[8:9], v[98:99], v[4:5]
	s_waitcnt lgkmcnt(0)
	v_mul_f32_e32 v4, 0x3fb8aa3b, v7
	v_exp_f32_e32 v7, v4
	v_mul_f32_e32 v6, 0x3fb8aa3b, v6
	v_exp_f32_e32 v6, v6
	s_nop 0
	v_pk_mul_f32 v[4:5], v[8:9], v[6:7]
	v_rcp_f32_e32 v10, v7
	s_nop 0
	v_mul_f32_e32 v10, v9, v10
	s_nop 0
	v_rcp_f32_e32 v7, v6
	s_nop 0
	v_mul_f32_e32 v11, v8, v7
	v_add_u32_e32 v6, 0x30c8, v147
	ds_read2_b32 v[6:7], v6 offset1:1
	s_waitcnt lgkmcnt(0)
	v_mul_f32_e32 v7, 0x3fb8aa3b, v7
	v_exp_f32_e32 v7, v7
	v_mul_f32_e32 v6, 0x3fb8aa3b, v6
	v_exp_f32_e32 v6, v6
	s_nop 0
	v_pk_mul_f32 v[8:9], v[2:3], v[6:7]
	v_rcp_f32_e32 v12, v7
	s_nop 0
	v_mul_f32_e32 v7, v3, v12
	s_nop 0
	v_rcp_f32_e32 v3, v6
	s_nop 0
	v_mul_f32_e32 v6, v2, v3
	v_cvt_pk_bf16_f32 v2, v4, v5
	v_cvt_pk_bf16_f32 v3, v8, v9
	v_cvt_pk_bf16_f32 v4, v11, v10
	v_cvt_pk_bf16_f32 v5, v6, v7
	ds_write_b64 v140, v[2:3] offset:8064
	ds_write_b64 v141, v[4:5] offset:8064

; __global__ void __launch_bounds__(512) mega(Params P) {
;     ...
;         const int lane = tid & 63, gw = bid * 8 + (tid >> 6), nw = G * 8;
;         const float* fn = INP(32); const float* ssf = SS + (size_t)0 * T * 16; float* X = OUT;
;         for (int r = gw; r < T; r += nw) { const float rs = row_rstd(ssf, r);
; #pragma unroll
;             for (int i = 0; i < 4; ++i) { const size_t o = (size_t)r * D + i * 256 + lane * 4; *(f32x4*)(X + o) = *(const f32x4*)(X + o) * rs * *(const f32x4*)(fn + i * 256 + lane * 4); } }
.LBB0_845:
	s_mov_b32 s8, 0
	s_and_b64 vcc, exec, s[4:5]
	s_cbranch_vccz .LBB0_850
	s_mov_b32 s8, s63
	v_mov_b32_e32 v6, v232
	s_mov_b32 s4, s2
	s_lshl_b32 s10, s4, 3
	v_ashrrev_i32_e32 v4, 6, v6
	v_add_u32_e32 v8, s10, v4
	s_mov_b32 s1, s3
	v_cmp_gt_i32_e32 vcc, s71, v8
	s_and_saveexec_b64 s[4:5], vcc
	s_cbranch_execz .LBB0_849
	s_ashr_i32 s9, s8, 31
	s_lshl_b32 s6, s1, 3
	s_lshl_b64 s[12:13], s[8:9], 2
	v_readlane_b32 s16, v252, 0
	v_readlane_b32 s17, v252, 1
	s_add_u32 s14, s16, s12
	s_addc_u32 s15, s17, s13
	v_ashrrev_i32_e32 v5, 31, v4
	s_ashr_i32 s11, s10, 31
	v_readlane_b32 s1, v254, 61
	v_lshl_add_u64 v[10:11], v[4:5], 0, s[10:11]
	s_add_u32 s8, s1, s8
	v_readlane_b32 s1, v254, 62
	v_lshlrev_b32_e32 v0, 4, v6
	v_lshlrev_b64 v[4:5], 6, v[10:11]
	s_addc_u32 s9, s1, s9
	s_ashr_i32 s7, s6, 31
	v_and_b32_e32 v0, 0x3f0, v0
	v_lshl_add_u64 v[4:5], s[8:9], 0, v[4:5]
	s_lshl_b64 s[8:9], s[6:7], 6
	v_readlane_b32 s1, v254, 63
	v_lshl_add_u64 v[2:3], s[14:15], 0, v[0:1]
	v_lshlrev_b64 v[10:11], 12, v[10:11]
	v_and_b32_e32 v0, 63, v6
	s_add_u32 s10, s1, s12
	v_readlane_b32 s1, v255, 0
	v_lshl_or_b32 v10, v0, 4, v10
	s_addc_u32 s11, s1, s13
	v_lshl_add_u64 v[6:7], s[10:11], 0, v[10:11]
	s_lshl_b64 s[10:11], s[6:7], 12
	s_mov_b64 s[12:13], 0
	v_readlane_b32 s18, v252, 2
	v_readlane_b32 s19, v252, 3
	global_load_dwordx4 v[40:43], v[2:3], off
	global_load_dwordx4 v[44:47], v[2:3], off offset:1024
	global_load_dwordx4 v[48:51], v[2:3], off offset:2048
	global_load_dwordx4 v[52:55], v[2:3], off offset:3072
.LBB0_848:
	global_load_dwordx4 v[10:13], v[4:5], off offset:-32
	global_load_dwordx4 v[14:17], v[4:5], off
	global_load_dwordx4 v[18:21], v[4:5], off offset:-16
	global_load_dwordx4 v[22:25], v[4:5], off offset:16
	global_load_dwordx4 v[26:29], v[6:7], off offset:-2048
	global_load_dwordx4 v[34:37], v[6:7], off offset:-1024
	global_load_dwordx4 v[56:59], v[6:7], off
	global_load_dwordx4 v[60:63], v[6:7], off offset:1024
	v_add_u32_e32 v8, s6, v8
	v_lshl_add_u64 v[4:5], v[4:5], 0, s[8:9]
	s_waitcnt vmcnt(4)
	v_mov_b32_e32 v38, v10
	v_mov_b32_e32 v39, v14
	v_mov_b32_e32 v14, v11
	v_mov_b32_e32 v10, v12
	v_mov_b32_e32 v11, v16
	v_mov_b32_e32 v16, v13
	v_mov_b32_e32 v12, v18
	v_mov_b32_e32 v13, v22
	v_mov_b32_e32 v22, v19
	v_mov_b32_e32 v18, v20
	v_mov_b32_e32 v19, v24
	v_mov_b32_e32 v24, v21
	v_pk_add_f32 v[14:15], v[38:39], v[14:15]
	v_pk_add_f32 v[10:11], v[10:11], v[16:17]
	v_pk_add_f32 v[12:13], v[12:13], v[22:23]
	v_pk_add_f32 v[16:17], v[18:19], v[24:25]
	v_pk_add_f32 v[10:11], v[14:15], v[10:11]
	v_pk_add_f32 v[12:13], v[12:13], v[16:17]
	s_nop 0
	v_pk_add_f32 v[10:11], v[10:11], v[12:13]
	s_nop 0
	v_add_f32_e32 v0, v10, v11
	v_fmamk_f32 v0, v0, 0x3a800000, v236
	v_mul_f32_e32 v9, 0x4b800000, v0
	v_cmp_gt_f32_e32 vcc, s76, v0
	s_nop 1
	v_cndmask_b32_e32 v0, v0, v9, vcc
	v_rsq_f32_e32 v0, v0
	s_nop 0
	v_mul_f32_e32 v9, 0x45800000, v0
	v_cndmask_b32_e32 v0, v0, v9, vcc
	v_cmp_lt_i32_e32 vcc, s95, v8
	s_or_b64 s[12:13], vcc, s[12:13]
	s_waitcnt vmcnt(0)
	v_pk_mul_f32 v[10:11], v[0:1], v[26:27] op_sel_hi:[0,1]
	v_pk_mul_f32 v[12:13], v[0:1], v[28:29] op_sel_hi:[0,1]
	v_pk_mul_f32 v[12:13], v[12:13], v[42:43]
	v_pk_mul_f32 v[10:11], v[10:11], v[40:41]
	global_store_dwordx4 v[6:7], v[10:13], off offset:-2048
	s_nop 1
	v_pk_mul_f32 v[10:11], v[0:1], v[34:35] op_sel_hi:[0,1]
	v_pk_mul_f32 v[12:13], v[0:1], v[36:37] op_sel_hi:[0,1]
	v_pk_mul_f32 v[12:13], v[12:13], v[46:47]
	v_pk_mul_f32 v[10:11], v[10:11], v[44:45]
	global_store_dwordx4 v[6:7], v[10:13], off offset:-1024
	s_nop 1
	v_pk_mul_f32 v[10:11], v[0:1], v[56:57] op_sel_hi:[0,1]
	v_pk_mul_f32 v[12:13], v[0:1], v[58:59] op_sel_hi:[0,1]
	v_pk_mul_f32 v[12:13], v[12:13], v[50:51]
	v_pk_mul_f32 v[10:11], v[10:11], v[48:49]
	global_store_dwordx4 v[6:7], v[10:13], off
	s_nop 1
	v_pk_mul_f32 v[10:11], v[0:1], v[60:61] op_sel_hi:[0,1]
	v_pk_mul_f32 v[12:13], v[0:1], v[62:63] op_sel_hi:[0,1]
	v_pk_mul_f32 v[12:13], v[12:13], v[54:55]
	v_pk_mul_f32 v[10:11], v[10:11], v[52:53]
	global_store_dwordx4 v[6:7], v[10:13], off offset:1024
	s_nop 1
	v_lshl_add_u64 v[6:7], v[6:7], 0, s[10:11]
	s_andn2_b64 exec, exec, s[12:13]
	s_cbranch_execnz .LBB0_848
